# conversion split plus larger half-skew in out-projection (22us) and GLU (10us), where the delayed half has a spare round
# baseline (speedup 1.0000x reference)
.LBB0_879:
	s_or_b64 exec, exec, s[4:5]
	v_readlane_b32 s88, v254, 10
	v_readlane_b32 s89, v254, 11
	s_waitcnt lgkmcnt(0)
	v_mov_b32_e32 v1, v0
	s_mov_b64 s[0:1], s[88:89]
	s_barrier
	s_load_dwordx2 s[8:9], s[0:1], 0xd0
	s_load_dwordx2 s[4:5], s[0:1], 0x108
	s_and_b64 vcc, exec, s[64:65]
	v_readlane_b32 s62, v254, 24
	v_readlane_b32 s63, v254, 25
	s_cbranch_vccz .LBB0_883
	s_memrealtime s[0:1]
	s_memrealtime s[2:3]
	v_mov_b64_e32 v[2:3], 0x3e7
	s_waitcnt lgkmcnt(0)
	s_sub_u32 s2, s2, s0
	s_subb_u32 s3, s3, s1
	v_cmp_gt_u64_e32 vcc, s[2:3], v[2:3]
	s_cbranch_vccnz .LBB0_883
	v_mov_b64_e32 v[2:3], 0x3e8

.LBB0_952:
	s_or_b64 exec, exec, s[4:5]
	s_waitcnt lgkmcnt(0)
	v_mov_b32_e32 v1, v0
	s_mov_b64 s[0:1], s[88:89]
	s_barrier
	s_load_dwordx2 s[12:13], s[0:1], 0x108
	s_load_dwordx4 s[8:11], s[0:1], 0x0
	s_load_dwordx2 s[14:15], s[0:1], 0xe0
	v_readfirstlane_b32 s2, v1
	s_and_b64 vcc, exec, s[64:65]
	s_cbranch_vccz .LBB0_956
	s_memrealtime s[0:1]
	s_memrealtime s[4:5]
	v_mov_b64_e32 v[2:3], 0x897
	s_waitcnt lgkmcnt(0)
	s_sub_u32 s4, s4, s0
	s_subb_u32 s5, s5, s1
	v_cmp_gt_u64_e32 vcc, s[4:5], v[2:3]
	s_cbranch_vccnz .LBB0_956
	v_mov_b64_e32 v[2:3], 0x898
